# diff loop: the tile's 8 V fragments are read from LDS once (phase X) and kept in registers for PV2 in phase Y
# speedup vs baseline: 1.0196x; 1.0196x over previous
.Ldiff_nodma:
	s_and_b32 s19, s15, 3
	s_lshl_b32 s19, s19, 14
	s_add_i32 s20, s15, 1
	s_and_b32 s20, s20, 3
	s_lshl_b32 s20, s20, 14
	v_add_u32_e32 v221, s19, v204
	v_add_u32_e32 v219, s20, v200
	v_add_u32_e32 v220, s20, v201
	ds_read_b64_tr_b16 v[156:157], v221 offset:8192
	ds_read_b64_tr_b16 v[158:159], v221 offset:9216
	ds_read_b64_tr_b16 v[162:163], v221 offset:8704
	ds_read_b64_tr_b16 v[164:165], v221 offset:9728
	ds_read_b64_tr_b16 v[174:175], v221 offset:10240
	ds_read_b64_tr_b16 v[176:177], v221 offset:11264
	ds_read_b128 v[112:115], v219
	ds_read_b128 v[116:119], v219 offset:4096
	ds_read_b128 v[148:151], v220
	ds_read_b128 v[152:155], v220 offset:4096
	v_exp_f32_e32 v132, v132
	v_exp_f32_e32 v133, v133
	v_exp_f32_e32 v134, v134
	v_exp_f32_e32 v135, v135
	s_waitcnt lgkmcnt(8)
	v_mfma_f32_32x32x16_bf16 v[32:47], v[156:159], v[64:67], v[32:47]
	ds_read_b64_tr_b16 v[178:179], v221 offset:10752
	ds_read_b64_tr_b16 v[180:181], v221 offset:11776
	v_exp_f32_e32 v136, v136
	v_exp_f32_e32 v137, v137
	v_exp_f32_e32 v138, v138
	v_exp_f32_e32 v139, v139
	v_exp_f32_e32 v140, v140
	v_exp_f32_e32 v141, v141
	v_exp_f32_e32 v142, v142
	s_waitcnt lgkmcnt(8)
	v_mfma_f32_32x32x16_bf16 v[0:15], v[162:165], v[64:67], v[0:15]
	ds_read_b64_tr_b16 v[224:225], v221 offset:12288
	ds_read_b64_tr_b16 v[226:227], v221 offset:13312
	v_exp_f32_e32 v143, v143
	v_exp_f32_e32 v144, v144
	v_exp_f32_e32 v145, v145
	v_exp_f32_e32 v146, v146
	v_exp_f32_e32 v147, v147
	v_add_f32_e32 v129, v132, v129
	s_waitcnt lgkmcnt(8)
	v_mfma_f32_32x32x16_bf16 v[32:47], v[174:177], v[68:71], v[32:47]
	ds_read_b64_tr_b16 v[228:229], v221 offset:12800
	ds_read_b64_tr_b16 v[230:231], v221 offset:13824
	v_add_f32_e32 v131, v133, v131
	v_add_f32_e32 v129, v134, v129
	v_add_f32_e32 v131, v135, v131
	v_add_f32_e32 v129, v136, v129
	v_add_f32_e32 v131, v137, v131
	v_add_f32_e32 v129, v138, v129
	v_add_f32_e32 v131, v139, v131
	s_waitcnt lgkmcnt(4)
	v_mfma_f32_32x32x16_bf16 v[0:15], v[178:181], v[68:71], v[0:15]
	ds_read_b64_tr_b16 v[232:233], v221 offset:14336
	ds_read_b64_tr_b16 v[234:235], v221 offset:15360
	v_add_f32_e32 v129, v140, v129
	v_add_f32_e32 v131, v141, v131
	v_add_f32_e32 v129, v142, v129
	v_add_f32_e32 v131, v143, v131
	v_add_f32_e32 v129, v144, v129
	v_add_f32_e32 v131, v145, v131
	s_waitcnt lgkmcnt(4)
	v_mfma_f32_32x32x16_bf16 v[32:47], v[224:227], v[96:99], v[32:47]
	ds_read_b64_tr_b16 v[236:237], v221 offset:14848
	ds_read_b64_tr_b16 v[238:239], v221 offset:15872
	v_add_f32_e32 v129, v146, v129
	v_add_f32_e32 v131, v147, v131
	v_cvt_pk_bf16_f32 v132, v132, v133
	v_cvt_pk_bf16_f32 v133, v134, v135
	v_cvt_pk_bf16_f32 v134, v136, v137
	v_cvt_pk_bf16_f32 v135, v138, v139
	v_cvt_pk_bf16_f32 v136, v140, v141
	s_waitcnt lgkmcnt(4)
	v_mfma_f32_32x32x16_bf16 v[0:15], v[228:231], v[96:99], v[0:15]
	v_cvt_pk_bf16_f32 v137, v142, v143
	v_cvt_pk_bf16_f32 v138, v144, v145
	v_cvt_pk_bf16_f32 v139, v146, v147
	v_exp_f32_e32 v184, v184
	v_exp_f32_e32 v185, v185
	v_exp_f32_e32 v186, v186
	s_waitcnt lgkmcnt(2)
	v_mfma_f32_32x32x16_bf16 v[32:47], v[232:235], v[100:103], v[32:47]
	v_exp_f32_e32 v187, v187
	v_exp_f32_e32 v188, v188
	v_exp_f32_e32 v189, v189
	v_exp_f32_e32 v190, v190
	v_exp_f32_e32 v191, v191
	v_exp_f32_e32 v192, v192
	v_exp_f32_e32 v193, v193
	s_waitcnt lgkmcnt(0)
	v_mfma_f32_32x32x16_bf16 v[0:15], v[236:239], v[100:103], v[0:15]
	v_exp_f32_e32 v194, v194
	v_exp_f32_e32 v195, v195
	v_exp_f32_e32 v196, v196
	v_exp_f32_e32 v197, v197
	v_exp_f32_e32 v198, v198
	v_exp_f32_e32 v199, v199
	s_waitcnt lgkmcnt(10)
	v_mfma_f32_32x32x16_bf16 v[64:79], v[112:115], v[80:83], 0
	v_add_f32_e32 v129, v184, v129
	v_add_f32_e32 v131, v185, v131
	v_add_f32_e32 v129, v186, v129
	v_add_f32_e32 v131, v187, v131
	v_add_f32_e32 v129, v188, v129
	v_add_f32_e32 v131, v189, v131
	v_add_f32_e32 v129, v190, v129
	v_mfma_f32_32x32x16_bf16 v[96:111], v[116:119], v[80:83], 0
	v_add_f32_e32 v131, v191, v131
	v_add_f32_e32 v129, v192, v129
	v_add_f32_e32 v131, v193, v131
	v_add_f32_e32 v129, v194, v129
	v_add_f32_e32 v131, v195, v131
	v_add_f32_e32 v129, v196, v129
	v_mfma_f32_32x32x16_bf16 v[64:79], v[148:151], v[84:87], v[64:79]
	v_add_f32_e32 v131, v197, v131
	v_add_f32_e32 v129, v198, v129
	v_add_f32_e32 v131, v199, v131
	v_cvt_pk_bf16_f32 v184, v184, v185
	v_cvt_pk_bf16_f32 v185, v186, v187
	v_cvt_pk_bf16_f32 v186, v188, v189
	v_cvt_pk_bf16_f32 v187, v190, v191
	v_mfma_f32_32x32x16_bf16 v[96:111], v[152:155], v[84:87], v[96:111]
	v_cvt_pk_bf16_f32 v188, v192, v193
	v_cvt_pk_bf16_f32 v189, v194, v195
	v_cvt_pk_bf16_f32 v190, v196, v197
	v_cvt_pk_bf16_f32 v191, v198, v199
	v_add_u32_e32 v219, s20, v202
	v_add_u32_e32 v220, s20, v203
	ds_read_b128 v[112:115], v219
	ds_read_b128 v[116:119], v219 offset:4096
	ds_read_b128 v[148:151], v220
	ds_read_b128 v[152:155], v220 offset:4096
	v_exp_f32_e32 v64, v64
	v_exp_f32_e32 v65, v65
	v_exp_f32_e32 v66, v66
	v_exp_f32_e32 v67, v67
	v_mfma_f32_32x32x16_bf16 v[48:63], v[156:159], v[132:135], v[48:63]
	v_exp_f32_e32 v68, v68
	v_exp_f32_e32 v69, v69
	v_exp_f32_e32 v70, v70
	v_exp_f32_e32 v71, v71
	v_exp_f32_e32 v72, v72
	v_exp_f32_e32 v73, v73
	v_exp_f32_e32 v74, v74
	v_mfma_f32_32x32x16_bf16 v[16:31], v[162:165], v[132:135], v[16:31]
	v_exp_f32_e32 v75, v75
	v_exp_f32_e32 v76, v76
	v_exp_f32_e32 v77, v77
	v_exp_f32_e32 v78, v78
	v_exp_f32_e32 v79, v79
	v_add_f32_e32 v128, v64, v128
	v_mfma_f32_32x32x16_bf16 v[48:63], v[174:177], v[136:139], v[48:63]
	v_add_f32_e32 v130, v65, v130
	v_add_f32_e32 v128, v66, v128
	v_add_f32_e32 v130, v67, v130
	v_add_f32_e32 v128, v68, v128
	v_add_f32_e32 v130, v69, v130
	v_add_f32_e32 v128, v70, v128
	v_add_f32_e32 v130, v71, v130
	v_mfma_f32_32x32x16_bf16 v[16:31], v[178:181], v[136:139], v[16:31]
	v_add_f32_e32 v128, v72, v128
	v_add_f32_e32 v130, v73, v130
	v_add_f32_e32 v128, v74, v128
	v_add_f32_e32 v130, v75, v130
	v_add_f32_e32 v128, v76, v128
	v_add_f32_e32 v130, v77, v130
	v_mfma_f32_32x32x16_bf16 v[48:63], v[224:227], v[184:187], v[48:63]
	v_add_f32_e32 v128, v78, v128
	v_add_f32_e32 v130, v79, v130
	v_cvt_pk_bf16_f32 v64, v64, v65
	v_cvt_pk_bf16_f32 v65, v66, v67
	v_cvt_pk_bf16_f32 v66, v68, v69
	v_cvt_pk_bf16_f32 v67, v70, v71
	v_cvt_pk_bf16_f32 v68, v72, v73
	v_mfma_f32_32x32x16_bf16 v[16:31], v[228:231], v[184:187], v[16:31]
	v_cvt_pk_bf16_f32 v69, v74, v75
	v_cvt_pk_bf16_f32 v70, v76, v77
	v_cvt_pk_bf16_f32 v71, v78, v79
	v_exp_f32_e32 v96, v96
	v_exp_f32_e32 v97, v97
	v_exp_f32_e32 v98, v98
	v_mfma_f32_32x32x16_bf16 v[48:63], v[232:235], v[188:191], v[48:63]
	v_exp_f32_e32 v99, v99
	v_exp_f32_e32 v100, v100
	v_exp_f32_e32 v101, v101
	v_exp_f32_e32 v102, v102
	v_exp_f32_e32 v103, v103
	v_exp_f32_e32 v104, v104
	v_exp_f32_e32 v105, v105
	v_mfma_f32_32x32x16_bf16 v[16:31], v[236:239], v[188:191], v[16:31]
	v_exp_f32_e32 v106, v106
	v_exp_f32_e32 v107, v107
	v_exp_f32_e32 v108, v108
	v_exp_f32_e32 v109, v109
	v_exp_f32_e32 v110, v110
	v_exp_f32_e32 v111, v111
	s_waitcnt lgkmcnt(0)
	v_mfma_f32_32x32x16_bf16 v[132:147], v[112:115], v[88:91], 0
	v_add_f32_e32 v128, v96, v128
	v_add_f32_e32 v130, v97, v130
	v_add_f32_e32 v128, v98, v128
	v_add_f32_e32 v130, v99, v130
	v_add_f32_e32 v128, v100, v128
	v_add_f32_e32 v130, v101, v130
	v_add_f32_e32 v128, v102, v128
	v_mfma_f32_32x32x16_bf16 v[184:199], v[116:119], v[88:91], 0
	v_add_f32_e32 v130, v103, v130
	v_add_f32_e32 v128, v104, v128
	v_add_f32_e32 v130, v105, v130
	v_add_f32_e32 v128, v106, v128
	v_add_f32_e32 v130, v107, v130
	v_add_f32_e32 v128, v108, v128
	v_mfma_f32_32x32x16_bf16 v[132:147], v[148:151], v[92:95], v[132:147]
	v_add_f32_e32 v130, v109, v130
	v_add_f32_e32 v128, v110, v128
	v_add_f32_e32 v130, v111, v130
	v_cvt_pk_bf16_f32 v96, v96, v97
	v_cvt_pk_bf16_f32 v97, v98, v99
	v_cvt_pk_bf16_f32 v98, v100, v101
	v_cvt_pk_bf16_f32 v99, v102, v103
	v_mfma_f32_32x32x16_bf16 v[184:199], v[152:155], v[92:95], v[184:199]
	v_cvt_pk_bf16_f32 v100, v104, v105
	v_cvt_pk_bf16_f32 v101, v106, v107
	v_cvt_pk_bf16_f32 v102, v108, v109
	v_cvt_pk_bf16_f32 v103, v110, v111
	s_cmpk_lt_u32 s15, 0x81
	s_cbranch_scc0 .Ldiff_w0
	s_waitcnt vmcnt(2)
	s_branch .Ldiff_w1

.Ldiff_w1:
	s_barrier
	s_add_i32 s15, s15, 1
	s_add_i32 s17, s17, 64
	s_cmpk_lt_u32 s15, 0x83
	s_cbranch_scc1 .Ldiff_loop
	s_and_b32 s19, s15, 3
	s_lshl_b32 s19, s19, 14
	v_add_u32_e32 v221, s19, v204
	ds_read_b64_tr_b16 v[156:157], v221 offset:8192
	ds_read_b64_tr_b16 v[158:159], v221 offset:9216
	ds_read_b64_tr_b16 v[162:163], v221 offset:8704
	ds_read_b64_tr_b16 v[164:165], v221 offset:9728
	ds_read_b64_tr_b16 v[174:175], v221 offset:10240
	ds_read_b64_tr_b16 v[176:177], v221 offset:11264
	v_exp_f32_e32 v132, v132
	v_exp_f32_e32 v133, v133
	v_exp_f32_e32 v134, v134
	v_exp_f32_e32 v135, v135
	s_waitcnt lgkmcnt(4)
	v_mfma_f32_32x32x16_bf16 v[32:47], v[156:159], v[64:67], v[32:47]
	ds_read_b64_tr_b16 v[178:179], v221 offset:10752
	ds_read_b64_tr_b16 v[180:181], v221 offset:11776
	v_exp_f32_e32 v136, v136
	v_exp_f32_e32 v137, v137
	v_exp_f32_e32 v138, v138
	v_exp_f32_e32 v139, v139
	v_exp_f32_e32 v140, v140
	v_exp_f32_e32 v141, v141
	v_exp_f32_e32 v142, v142
	v_exp_f32_e32 v143, v143
	v_exp_f32_e32 v144, v144
	v_exp_f32_e32 v145, v145
	s_waitcnt lgkmcnt(4)
	v_mfma_f32_32x32x16_bf16 v[0:15], v[162:165], v[64:67], v[0:15]
	ds_read_b64_tr_b16 v[224:225], v221 offset:12288
	ds_read_b64_tr_b16 v[226:227], v221 offset:13312
	v_exp_f32_e32 v146, v146
	v_exp_f32_e32 v147, v147
	v_add_f32_e32 v129, v132, v129
	v_add_f32_e32 v131, v133, v131
	v_add_f32_e32 v129, v134, v129
	v_add_f32_e32 v131, v135, v131
	v_add_f32_e32 v129, v136, v129
	v_add_f32_e32 v131, v137, v131
	v_add_f32_e32 v129, v138, v129
	v_add_f32_e32 v131, v139, v131
	v_add_f32_e32 v129, v140, v129
	s_waitcnt lgkmcnt(4)
	v_mfma_f32_32x32x16_bf16 v[32:47], v[174:177], v[68:71], v[32:47]
	ds_read_b64_tr_b16 v[228:229], v221 offset:12800
	ds_read_b64_tr_b16 v[230:231], v221 offset:13824
	v_add_f32_e32 v131, v141, v131
	v_add_f32_e32 v129, v142, v129
	v_add_f32_e32 v131, v143, v131
	v_add_f32_e32 v129, v144, v129
	v_add_f32_e32 v131, v145, v131
	v_add_f32_e32 v129, v146, v129
	v_add_f32_e32 v131, v147, v131
	v_cvt_pk_bf16_f32 v132, v132, v133
	v_cvt_pk_bf16_f32 v133, v134, v135
	v_cvt_pk_bf16_f32 v134, v136, v137
	s_waitcnt lgkmcnt(4)
	v_mfma_f32_32x32x16_bf16 v[0:15], v[178:181], v[68:71], v[0:15]
	ds_read_b64_tr_b16 v[232:233], v221 offset:14336
	ds_read_b64_tr_b16 v[234:235], v221 offset:15360
	v_cvt_pk_bf16_f32 v135, v138, v139
	v_cvt_pk_bf16_f32 v136, v140, v141
	v_cvt_pk_bf16_f32 v137, v142, v143
	v_cvt_pk_bf16_f32 v138, v144, v145
	v_cvt_pk_bf16_f32 v139, v146, v147
	v_exp_f32_e32 v184, v184
	v_exp_f32_e32 v185, v185
	v_exp_f32_e32 v186, v186
	v_exp_f32_e32 v187, v187
	v_exp_f32_e32 v188, v188
	s_waitcnt lgkmcnt(4)
	v_mfma_f32_32x32x16_bf16 v[32:47], v[224:227], v[96:99], v[32:47]
	ds_read_b64_tr_b16 v[236:237], v221 offset:14848
	ds_read_b64_tr_b16 v[238:239], v221 offset:15872
	v_exp_f32_e32 v189, v189
	v_exp_f32_e32 v190, v190
	v_exp_f32_e32 v191, v191
	v_exp_f32_e32 v192, v192
	v_exp_f32_e32 v193, v193
	v_exp_f32_e32 v194, v194
	v_exp_f32_e32 v195, v195
	v_exp_f32_e32 v196, v196
	v_exp_f32_e32 v197, v197
	v_exp_f32_e32 v198, v198
	s_waitcnt lgkmcnt(4)
	v_mfma_f32_32x32x16_bf16 v[0:15], v[228:231], v[96:99], v[0:15]
	v_exp_f32_e32 v199, v199
	v_add_f32_e32 v129, v184, v129
	v_add_f32_e32 v131, v185, v131
	v_add_f32_e32 v129, v186, v129
	v_add_f32_e32 v131, v187, v131
	v_add_f32_e32 v129, v188, v129
	v_add_f32_e32 v131, v189, v131
	v_add_f32_e32 v129, v190, v129
	v_add_f32_e32 v131, v191, v131
	v_add_f32_e32 v129, v192, v129
	v_add_f32_e32 v131, v193, v131
	s_waitcnt lgkmcnt(2)
	v_mfma_f32_32x32x16_bf16 v[32:47], v[232:235], v[100:103], v[32:47]
	v_add_f32_e32 v129, v194, v129
	v_add_f32_e32 v131, v195, v131
	v_add_f32_e32 v129, v196, v129
	v_add_f32_e32 v131, v197, v131
	v_add_f32_e32 v129, v198, v129
	v_add_f32_e32 v131, v199, v131
	v_cvt_pk_bf16_f32 v184, v184, v185
	v_cvt_pk_bf16_f32 v185, v186, v187
	v_cvt_pk_bf16_f32 v186, v188, v189
	v_cvt_pk_bf16_f32 v187, v190, v191
	s_waitcnt lgkmcnt(0)
	v_mfma_f32_32x32x16_bf16 v[0:15], v[236:239], v[100:103], v[0:15]
	v_cvt_pk_bf16_f32 v188, v192, v193
	v_cvt_pk_bf16_f32 v189, v194, v195
	v_cvt_pk_bf16_f32 v190, v196, v197
	v_cvt_pk_bf16_f32 v191, v198, v199
	v_mfma_f32_32x32x16_bf16 v[48:63], v[156:159], v[132:135], v[48:63]
	v_mfma_f32_32x32x16_bf16 v[16:31], v[162:165], v[132:135], v[16:31]
	v_mfma_f32_32x32x16_bf16 v[48:63], v[174:177], v[136:139], v[48:63]
	v_mfma_f32_32x32x16_bf16 v[16:31], v[178:181], v[136:139], v[16:31]
	v_mfma_f32_32x32x16_bf16 v[48:63], v[224:227], v[184:187], v[48:63]
	v_mfma_f32_32x32x16_bf16 v[16:31], v[228:231], v[184:187], v[16:31]
	v_mfma_f32_32x32x16_bf16 v[48:63], v[232:235], v[188:191], v[48:63]
	v_mfma_f32_32x32x16_bf16 v[16:31], v[236:239], v[188:191], v[16:31]
	s_barrier
	s_setprio 0
	v_add_f32_e32 v128, v128, v130
	v_add_f32_e32 v129, v129, v131
	s_branch .LBB0_561
